# MLA units: merge-gate rows prefetched in the unit prologue instead of loaded in the epilogue
# baseline (speedup 1.0000x reference)
.LBB0_966:
	s_lshl_b64 s[12:13], s[0:1], 10
	s_add_u32 s7, s16, s12
	s_addc_u32 s12, s17, s13
	s_lshl_b32 s13, s6, 1
	s_add_u32 s6, s7, s13
	s_addc_u32 s7, s12, 0
	s_lshl_b64 s[0:1], s[0:1], 11
	s_add_u32 s0, s26, s0
	s_addc_u32 s1, s27, s1
	s_add_u32 s0, s0, s13
	s_addc_u32 s1, s1, 0
	s_setprio 0
	v_pk_add_f32 v[34:35], v[172:173], v[172:173] op_sel:[0,1] op_sel_hi:[1,0]
	s_nop 0
	v_mov_b32_e32 v0, v34
	s_nop 1
	v_permlane32_swap_b32_e32 v34, v0
	v_add_f32_e32 v36, v34, v0
	v_lshlrev_b32_e32 v0, 10, v163
	v_lshl_add_u64 v[34:35], s[6:7], 0, v[0:1]
	v_lshlrev_b32_e32 v0, 11, v163
	v_mov_b32_e32 v163, v1
	v_lshl_add_u64 v[34:35], v[34:35], 0, v[162:163]
	v_mov_b64_e32 v[48:49], v[236:237]
	v_mov_b64_e32 v[50:51], v[238:239]
	v_mov_b64_e32 v[46:47], v[240:241]
	v_mov_b64_e32 v[44:45], v[242:243]
	v_mov_b64_e32 v[42:43], v[244:245]
	v_mov_b64_e32 v[40:41], v[246:247]
	v_mov_b64_e32 v[38:39], v[248:249]
	s_nop 0
	v_mov_b64_e32 v[34:35], v[250:251]
	v_div_scale_f32 v37, s[6:7], v36, v36, 1.0
	v_rcp_f32_e32 v52, v37
	s_nop 0
	v_fma_f32 v53, -v37, v52, 1.0
	v_fmac_f32_e32 v52, v53, v52
	v_div_scale_f32 v53, vcc, 1.0, v36, 1.0
	v_mul_f32_e32 v54, v53, v52
	v_fma_f32 v55, -v37, v54, v53
	v_fmac_f32_e32 v54, v55, v52
	v_fma_f32 v37, -v37, v54, v53
	v_div_fmas_f32 v37, v37, v52, v54
	v_div_fixup_f32 v36, v37, v36, 1.0
	v_pk_mul_f32 v[20:21], v[20:21], v[36:37] op_sel_hi:[1,0]
	v_pk_mul_f32 v[18:19], v[18:19], v[36:37] op_sel_hi:[1,0]
	v_lshl_add_u64 v[52:53], s[0:1], 0, v[0:1]
	v_pk_mul_f32 v[2:3], v[2:3], v[36:37] op_sel_hi:[1,0]
	v_pk_mul_f32 v[4:5], v[4:5], v[36:37] op_sel_hi:[1,0]
	s_nop 0
	v_lshlrev_b32_e32 v54, 16, v48
	v_and_b32_e32 v55, 0xffff0000, v48
	v_lshlrev_b32_e32 v48, 16, v49
	v_and_b32_e32 v49, 0xffff0000, v49
	v_pk_mul_f32 v[20:21], v[20:21], v[48:49]
	v_pk_mul_f32 v[18:19], v[18:19], v[54:55]
	v_cvt_pk_bf16_f32 v49, v20, v21
	v_pk_mul_f32 v[20:21], v[22:23], v[36:37] op_sel_hi:[1,0]
	s_nop 0
	v_lshlrev_b32_e32 v22, 16, v50
	v_and_b32_e32 v23, 0xffff0000, v50
	v_pk_mul_f32 v[20:21], v[20:21], v[22:23]
	v_pk_mul_f32 v[22:23], v[24:25], v[36:37] op_sel_hi:[1,0]
	v_lshlrev_b32_e32 v24, 16, v51
	v_and_b32_e32 v25, 0xffff0000, v51
	v_pk_mul_f32 v[22:23], v[22:23], v[24:25]
	v_cvt_pk_bf16_f32 v48, v18, v19
	v_lshl_add_u64 v[18:19], v[52:53], 0, v[162:163]
	v_cvt_pk_bf16_f32 v20, v20, v21
	v_cvt_pk_bf16_f32 v21, v22, v23
	global_store_dwordx2 v[18:19], v[20:21], off offset:16
	v_pk_mul_f32 v[20:21], v[26:27], v[36:37] op_sel_hi:[1,0]
	s_nop 0
	v_lshlrev_b32_e32 v22, 16, v46
	v_and_b32_e32 v23, 0xffff0000, v46
	v_pk_mul_f32 v[20:21], v[20:21], v[22:23]
	v_pk_mul_f32 v[22:23], v[28:29], v[36:37] op_sel_hi:[1,0]
	v_lshlrev_b32_e32 v24, 16, v47
	v_and_b32_e32 v25, 0xffff0000, v47
	v_pk_mul_f32 v[22:23], v[22:23], v[24:25]
	v_cvt_pk_bf16_f32 v20, v20, v21
	v_cvt_pk_bf16_f32 v21, v22, v23
	global_store_dwordx2 v[18:19], v[20:21], off offset:32
	v_pk_mul_f32 v[20:21], v[30:31], v[36:37] op_sel_hi:[1,0]
	s_nop 0
	v_lshlrev_b32_e32 v22, 16, v44
	v_and_b32_e32 v23, 0xffff0000, v44
	v_pk_mul_f32 v[20:21], v[20:21], v[22:23]
	v_pk_mul_f32 v[22:23], v[32:33], v[36:37] op_sel_hi:[1,0]
	v_lshlrev_b32_e32 v24, 16, v45
	v_and_b32_e32 v25, 0xffff0000, v45
	v_pk_mul_f32 v[22:23], v[22:23], v[24:25]
	v_cvt_pk_bf16_f32 v20, v20, v21
	v_cvt_pk_bf16_f32 v21, v22, v23
	global_store_dwordx2 v[18:19], v[20:21], off offset:48
	s_nop 0
	v_lshlrev_b32_e32 v20, 16, v42
	v_and_b32_e32 v21, 0xffff0000, v42
	v_pk_mul_f32 v[2:3], v[2:3], v[20:21]
	v_lshlrev_b32_e32 v20, 16, v43
	v_and_b32_e32 v21, 0xffff0000, v43
	v_pk_mul_f32 v[4:5], v[4:5], v[20:21]
	v_cvt_pk_bf16_f32 v2, v2, v3
	v_cvt_pk_bf16_f32 v3, v4, v5
	global_store_dwordx2 v[18:19], v[2:3], off offset:64
	v_pk_mul_f32 v[2:3], v[6:7], v[36:37] op_sel_hi:[1,0]
	s_nop 0
	v_lshlrev_b32_e32 v4, 16, v40
	v_and_b32_e32 v5, 0xffff0000, v40
	v_pk_mul_f32 v[2:3], v[2:3], v[4:5]
	v_pk_mul_f32 v[4:5], v[8:9], v[36:37] op_sel_hi:[1,0]
	v_lshlrev_b32_e32 v6, 16, v41
	v_and_b32_e32 v7, 0xffff0000, v41
	v_pk_mul_f32 v[4:5], v[4:5], v[6:7]
	v_cvt_pk_bf16_f32 v2, v2, v3
	v_cvt_pk_bf16_f32 v3, v4, v5
	global_store_dwordx2 v[18:19], v[2:3], off offset:80
	v_pk_mul_f32 v[2:3], v[10:11], v[36:37] op_sel_hi:[1,0]
	s_nop 0
	v_lshlrev_b32_e32 v4, 16, v38
	v_and_b32_e32 v5, 0xffff0000, v38
	v_pk_mul_f32 v[2:3], v[2:3], v[4:5]
	v_pk_mul_f32 v[4:5], v[12:13], v[36:37] op_sel_hi:[1,0]
	v_lshlrev_b32_e32 v6, 16, v39
	v_and_b32_e32 v7, 0xffff0000, v39
	v_pk_mul_f32 v[4:5], v[4:5], v[6:7]
	v_cvt_pk_bf16_f32 v2, v2, v3
	v_cvt_pk_bf16_f32 v3, v4, v5
	global_store_dwordx2 v[18:19], v[2:3], off offset:96
	v_pk_mul_f32 v[2:3], v[14:15], v[36:37] op_sel_hi:[1,0]
	s_nop 0
	v_lshlrev_b32_e32 v4, 16, v34
	v_and_b32_e32 v5, 0xffff0000, v34
	v_pk_mul_f32 v[2:3], v[2:3], v[4:5]
	v_pk_mul_f32 v[4:5], v[16:17], v[36:37] op_sel_hi:[1,0]
	v_lshlrev_b32_e32 v6, 16, v35
	v_and_b32_e32 v7, 0xffff0000, v35
	v_pk_mul_f32 v[4:5], v[4:5], v[6:7]
	v_cvt_pk_bf16_f32 v2, v2, v3
	v_cvt_pk_bf16_f32 v3, v4, v5
	global_store_dwordx2 v[18:19], v[48:49], off
	global_store_dwordx2 v[18:19], v[2:3], off offset:112

.Ldma_sdone_2:
	v_lshrrev_b32_e32 v207, 2, v163
	v_lshrrev_b32_e32 v201, 3, v163
	v_xor_b32_e32 v207, v207, v201
	v_and_b32_e32 v207, 1, v207
	v_mul_u32_u24_e32 v207, 12, v207
	v_xor_b32_e32 v207, v163, v207
	v_mul_u32_u24_e32 v205, 0xd0, v207
	v_mul_u32_u24_e32 v206, 0x90, v163
	v_add_u32_e32 v206, 0x3400, v206
	v_add_u32_e32 v206, v206, v170
	v_add_u32_e32 v207, v205, v170
	v_add_u32_e32 v210, s67, v207
	v_add_u32_e32 v211, s67, v206
	s_lshl_b64 s[98:99], s[0:1], 10
	s_add_u32 s98, s16, s98
	s_addc_u32 s99, s17, s99
	s_lshl_b32 s32, s6, 1
	s_add_u32 s98, s98, s32
	s_addc_u32 s99, s99, 0
	v_lshlrev_b32_e32 v200, 10, v163
	v_add_u32_e32 v200, v200, v162
	global_load_dwordx2 v[236:237], v200, s[98:99]
	global_load_dwordx2 v[238:239], v200, s[98:99] offset:16
	global_load_dwordx2 v[240:241], v200, s[98:99] offset:32
	global_load_dwordx2 v[242:243], v200, s[98:99] offset:48
	global_load_dwordx2 v[244:245], v200, s[98:99] offset:64
	global_load_dwordx2 v[246:247], v200, s[98:99] offset:80
	global_load_dwordx2 v[248:249], v200, s[98:99] offset:96
	global_load_dwordx2 v[250:251], v200, s[98:99] offset:112
	s_mov_b32 m0, s60
	s_nop 0
	global_load_lds_dwordx4 v202, s[18:19]
	s_mov_b32 m0, s61
	s_nop 0
	global_load_lds_dwordx4 v203, s[18:19]
	s_mov_b32 m0, s66
	s_nop 0
	global_load_lds_dwordx4 v204, s[18:19]
	v_add_u32_e32 v202, v196, v202
	v_add_u32_e32 v203, v197, v203
	v_add_u32_e32 v204, v198, v204
	s_add_u32 m0, s60, 0x5800
	s_nop 0
	global_load_lds_dwordx4 v202, s[18:19]
	s_add_u32 m0, s61, 0x5800
	s_nop 0
	global_load_lds_dwordx4 v203, s[18:19]
	s_add_u32 m0, s66, 0x5800
	s_nop 0
	global_load_lds_dwordx4 v204, s[18:19]
	v_add_u32_e32 v202, v196, v202
	v_add_u32_e32 v203, v197, v203
	v_add_u32_e32 v204, v198, v204
	s_add_u32 m0, s60, 0xb000
	s_nop 0
	global_load_lds_dwordx4 v202, s[18:19]
	s_add_u32 m0, s61, 0xb000
	s_nop 0
	global_load_lds_dwordx4 v203, s[18:19]
	s_add_u32 m0, s66, 0xb000
	s_nop 0
	global_load_lds_dwordx4 v204, s[18:19]
	v_add_u32_e32 v202, v196, v202
	v_add_u32_e32 v203, v197, v203
	v_add_u32_e32 v204, v198, v204
	s_mov_b32 s13, 0
	s_waitcnt vmcnt(6)
	s_barrier
	s_branch .Ldma_top
